# P0 weight transposes: true double buffering (counted vmcnt(34) instead of vmcnt(0), gain-vector loads issued with the tile loads, exec-skip branches around tile loads removed)
# speedup vs baseline: 1.0497x; 1.0012x over previous
.LBB0_119:
	s_or_b64 exec, exec, s[22:23]
	v_readlane_b32 s25, v254, 56
	s_lshl_b32 s0, s25, 14
	s_add_i32 s22, s0, 0
	v_cmp_gt_u32_e64 s[0:1], 6, v20
	v_lshl_add_u32 v24, v20, 2, s22
	v_and_b32_e32 v20, 7, v74
	v_ashrrev_i32_e32 v80, 3, v74
	s_movk_i32 s24, 0x84
	v_lshlrev_b32_e32 v78, 3, v20
	v_mul_u32_u24_e32 v20, 0x420, v20
	v_lshlrev_b32_e32 v30, 2, v80
	v_mul_lo_u32 v28, v85, s24
	v_add3_u32 v87, s22, v20, v30
	s_lshl_b32 s22, s25, 5
	s_lshl_b32 s24, s25, 2
	s_lshl_b32 s25, s82, 8
	v_mov_b32_e32 v77, 0
	v_add_u32_e32 v82, 8, v80
	v_add_u32_e32 v84, 16, v80
	v_add_u32_e32 v86, 24, v80
	s_add_i32 s47, s10, s22
	s_lshl_b32 s49, s82, 6
	s_add_i32 s51, s25, s22
	s_lshl_b32 s22, s82, 5
	s_mov_b32 s23, 0
	v_ashrrev_i32_e32 v65, 31, v80
	v_ashrrev_i32_e32 v75, 31, v82
	v_ashrrev_i32_e32 v79, 31, v84
	v_ashrrev_i32_e32 v81, 31, v86
	s_lshl_b32 s45, s82, 4
	s_lshl_b32 s46, s80, 8
	s_lshl_b32 s48, s80, 5
	s_add_i32 s50, s49, s24
	s_add_i32 s52, s22, s24
	v_mov_b32_e32 v20, v77
	s_movk_i32 s53, 0x5800
	s_movk_i32 s54, 0x4018
	s_movk_i32 s55, 0x7fff
	s_mov_b32 s80, 0xffff0000
	v_lshlrev_b32_e32 v88, 1, v78
	v_add_u32_e32 v96, v24, v28
	s_mov_b32 s83, s4
	v_mov_b32_e32 v33, v77
	v_mov_b32_e32 v24, v77
	v_mov_b32_e32 v59, v77
	v_mov_b32_e32 v28, v77
	v_mov_b32_e32 v57, v77
	v_mov_b32_e32 v30, v77
	v_mov_b32_e32 v61, v77
	v_mov_b32_e32 v34, v77
	v_mov_b32_e32 v53, v77
	v_mov_b32_e32 v36, v77
	v_mov_b32_e32 v55, v77
	v_mov_b32_e32 v40, v77
	v_mov_b32_e32 v51, v77
	v_mov_b32_e32 v42, v77
	v_mov_b32_e32 v49, v77
	v_mov_b32_e32 v46, v77
	v_mov_b32_e32 v45, v77
	v_mov_b32_e32 v48, v77
	v_mov_b32_e32 v47, v77
	v_mov_b32_e32 v52, v77
	v_mov_b32_e32 v43, v77
	v_mov_b32_e32 v54, v77
	v_mov_b32_e32 v41, v77
	v_mov_b32_e32 v58, v77
	v_mov_b32_e32 v39, v77
	v_mov_b32_e32 v60, v77
	v_mov_b32_e32 v37, v77
	v_mov_b32_e32 v62, v77
	v_mov_b32_e32 v35, v77
	v_mov_b32_e32 v64, v77
	v_mov_b32_e32 v63, v77
	s_cmp_eq_u64 s[20:21], 0
	s_cselect_b32 s98, s16, s20
	s_cselect_b32 s99, s17, s21
	v_lshlrev_b32_e32 v114, 2, v78
	s_nop 3
	global_load_dwordx4 v[120:123], v114, s[98:99] offset:16
	global_load_dwordx4 v[116:119], v114, s[98:99]
	s_branch .LBB0_125
.Lp0_w1z:
	s_waitcnt vmcnt(0)
	s_branch .LBB0_227

.LBB0_120:
	s_or_b64 exec, exec, s[30:31]
	v_mov_b64_e32 v[90:91], s[26:27]
	s_cmp_eq_u64 s[20:21], 0
	s_cselect_b32 s98, s16, s20
	s_cselect_b32 s99, s17, s21
	v_lshlrev_b32_e32 v114, 2, v78
	s_nop 3
	global_load_dwordx4 v[120:123], v114, s[98:99] offset:16
	global_load_dwordx4 v[116:119], v114, s[98:99]
	s_waitcnt vmcnt(34)
.LBB0_121:
	ds_write2_b32 v97, v28, v57 offset0:8 offset1:74
	ds_write2_b32 v97, v30, v61 offset0:140 offset1:206
	ds_write2_b32 v98, v34, v53 offset0:16 offset1:82
	ds_write2_b32 v98, v36, v55 offset0:148 offset1:214
	ds_write2_b32 v99, v40, v51 offset0:24 offset1:90
	ds_write2_b32 v99, v42, v49 offset0:156 offset1:222
	ds_write2_b32 v100, v46, v45 offset0:32 offset1:98
	ds_write2_b32 v100, v48, v47 offset0:164 offset1:230
	ds_write2_b32 v101, v52, v43 offset0:40 offset1:106
	ds_write2_b32 v101, v54, v41 offset0:172 offset1:238
	ds_write2_b32 v102, v58, v39 offset0:48 offset1:114
	ds_write2_b32 v102, v60, v37 offset0:180 offset1:246
	ds_write2_b32 v103, v62, v35 offset0:56 offset1:122
	ds_write2_b32 v103, v64, v63 offset0:188 offset1:254
	ds_write2_b32 v96, v20, v33 offset1:66
	ds_write2_b32 v96, v24, v59 offset0:132 offset1:198
	s_waitcnt lgkmcnt(0)
	s_cmp_eq_u64 s[24:25], 0
	s_cbranch_scc1 .LBB0_139
	v_mov_b32_e32 v66, v128
	v_mov_b32_e32 v67, v129
	v_mov_b32_e32 v68, v130
	v_mov_b32_e32 v69, v131
	v_mov_b32_e32 v70, v124
	v_mov_b32_e32 v71, v125
	v_mov_b32_e32 v72, v126
	v_mov_b32_e32 v73, v127
	v_mov_b32_e32 v94, v67
	v_mov_b32_e32 v67, v68
	v_mov_b32_e32 v95, v69
	v_mov_b32_e32 v68, v71
	v_mov_b32_e32 v71, v72
	v_mov_b32_e32 v69, v73

.LBB0_162:
	s_xor_b64 s[34:35], s[34:35], -1
	v_mov_b32_e32 v20, s23
	s_and_saveexec_b64 s[38:39], s[34:35]
	s_xor_b64 s[38:39], exec, s[38:39]
	v_mov_b32_e32 v33, s23
	s_or_saveexec_b64 s[38:39], s[38:39]
	v_lshl_add_u64 v[66:67], v[66:67], 0, v[76:77]
	s_xor_b64 exec, exec, s[38:39]
	v_lshl_add_u64 v[34:35], s[30:31], 2, v[66:67]
	global_load_dword v20, v[66:67], off
	global_load_dword v33, v[34:35], off
.LBB0_166:
	s_or_b64 exec, exec, s[38:39]
	v_mov_b32_e32 v24, s23
	s_and_saveexec_b64 s[38:39], s[34:35]
	s_xor_b64 s[38:39], exec, s[38:39]
	v_mov_b32_e32 v59, s23
	s_andn2_saveexec_b64 s[38:39], s[38:39]
	v_lshl_add_u64 v[58:59], s[30:31], 3, v[66:67]
	v_lshl_add_u64 v[68:69], s[30:31], 2, v[58:59]
	global_load_dword v24, v[58:59], off
	s_nop 0
	global_load_dword v59, v[68:69], off
.LBB0_170:
	s_or_b64 exec, exec, s[38:39]
	v_mov_b32_e32 v28, s23
	s_and_saveexec_b64 s[38:39], s[34:35]
	s_xor_b64 s[38:39], exec, s[38:39]
	v_mov_b32_e32 v57, s23
	s_andn2_saveexec_b64 s[38:39], s[38:39]
	v_lshl_add_u64 v[68:69], s[30:31], 4, v[66:67]
	v_lshl_add_u64 v[70:71], s[30:31], 2, v[68:69]
	global_load_dword v28, v[68:69], off
	global_load_dword v57, v[70:71], off
.LBB0_174:
	s_or_b64 exec, exec, s[38:39]
	v_mov_b32_e32 v30, s23
	s_and_saveexec_b64 s[38:39], s[34:35]
	s_xor_b64 s[38:39], exec, s[38:39]
	v_mov_b32_e32 v61, s23
	s_andn2_saveexec_b64 s[38:39], s[38:39]
	s_mul_i32 s22, s30, 24
	v_lshl_add_u64 v[60:61], v[66:67], 0, s[22:23]
	v_lshl_add_u64 v[68:69], s[30:31], 2, v[60:61]
	global_load_dword v30, v[60:61], off
	s_nop 0
	global_load_dword v61, v[68:69], off
.LBB0_178:
	s_or_b64 exec, exec, s[38:39]
	v_mov_b32_e32 v34, s23
	s_and_saveexec_b64 s[38:39], s[34:35]
	s_xor_b64 s[38:39], exec, s[38:39]
	v_mov_b32_e32 v53, s23
	s_andn2_saveexec_b64 s[38:39], s[38:39]
	s_lshl_b64 s[84:85], s[30:31], 5
	v_lshl_add_u64 v[52:53], v[66:67], 0, s[84:85]
	v_lshl_add_u64 v[68:69], s[30:31], 2, v[52:53]
	global_load_dword v34, v[52:53], off
	s_nop 0
	global_load_dword v53, v[68:69], off
.LBB0_182:
	s_or_b64 exec, exec, s[38:39]
	v_mov_b32_e32 v36, s23
	s_and_saveexec_b64 s[38:39], s[34:35]
	s_xor_b64 s[38:39], exec, s[38:39]
	v_mov_b32_e32 v55, s23
	s_andn2_saveexec_b64 s[38:39], s[38:39]
	s_mul_i32 s22, s30, 40
	v_lshl_add_u64 v[54:55], v[66:67], 0, s[22:23]
	v_lshl_add_u64 v[68:69], s[30:31], 2, v[54:55]
	global_load_dword v36, v[54:55], off
	s_nop 0
	global_load_dword v55, v[68:69], off
.LBB0_186:
	s_or_b64 exec, exec, s[38:39]
	v_mov_b32_e32 v40, s23
	s_and_saveexec_b64 s[38:39], s[34:35]
	s_xor_b64 s[38:39], exec, s[38:39]
	v_mov_b32_e32 v51, s23
	s_andn2_saveexec_b64 s[38:39], s[38:39]
	s_mul_i32 s22, s30, 48
	v_lshl_add_u64 v[68:69], v[66:67], 0, s[22:23]
	v_lshl_add_u64 v[70:71], s[30:31], 2, v[68:69]
	global_load_dword v40, v[68:69], off
	global_load_dword v51, v[70:71], off
.LBB0_190:
	s_or_b64 exec, exec, s[38:39]
	v_mov_b32_e32 v42, s23
	s_and_saveexec_b64 s[38:39], s[34:35]
	s_xor_b64 s[38:39], exec, s[38:39]
	v_mov_b32_e32 v49, s23
	s_andn2_saveexec_b64 s[38:39], s[38:39]
	s_mul_i32 s22, s30, 56
	v_lshl_add_u64 v[48:49], v[66:67], 0, s[22:23]
	v_lshl_add_u64 v[68:69], s[30:31], 2, v[48:49]
	global_load_dword v42, v[48:49], off
	s_nop 0
	global_load_dword v49, v[68:69], off
.LBB0_194:
	s_or_b64 exec, exec, s[38:39]
	v_mov_b32_e32 v46, s23
	s_and_saveexec_b64 s[38:39], s[34:35]
	s_xor_b64 s[38:39], exec, s[38:39]
	v_mov_b32_e32 v45, s23
	s_andn2_saveexec_b64 s[38:39], s[38:39]
	s_lshl_b64 s[84:85], s[30:31], 6
	v_lshl_add_u64 v[68:69], v[66:67], 0, s[84:85]
	v_lshl_add_u64 v[70:71], s[30:31], 2, v[68:69]
	global_load_dword v46, v[68:69], off
	global_load_dword v45, v[70:71], off
.LBB0_198:
	s_or_b64 exec, exec, s[38:39]
	v_mov_b32_e32 v48, s23
	s_and_saveexec_b64 s[38:39], s[34:35]
	s_xor_b64 s[38:39], exec, s[38:39]
	v_mov_b32_e32 v47, s23
	s_andn2_saveexec_b64 s[38:39], s[38:39]
	s_mul_i32 s22, s30, 0x48
	v_lshl_add_u64 v[68:69], v[66:67], 0, s[22:23]
	v_lshl_add_u64 v[70:71], s[30:31], 2, v[68:69]
	global_load_dword v48, v[68:69], off
	global_load_dword v47, v[70:71], off
.LBB0_202:
	s_or_b64 exec, exec, s[38:39]
	v_mov_b32_e32 v52, s23
	s_and_saveexec_b64 s[38:39], s[34:35]
	s_xor_b64 s[38:39], exec, s[38:39]
	v_mov_b32_e32 v43, s23
	s_andn2_saveexec_b64 s[38:39], s[38:39]
	s_mul_i32 s22, s30, 0x50
	v_lshl_add_u64 v[68:69], v[66:67], 0, s[22:23]
	v_lshl_add_u64 v[70:71], s[30:31], 2, v[68:69]
	global_load_dword v52, v[68:69], off
	global_load_dword v43, v[70:71], off
.LBB0_206:
	s_or_b64 exec, exec, s[38:39]
	v_mov_b32_e32 v54, s23
	s_and_saveexec_b64 s[38:39], s[34:35]
	s_xor_b64 s[38:39], exec, s[38:39]
	v_mov_b32_e32 v41, s23
	s_andn2_saveexec_b64 s[38:39], s[38:39]
	s_mul_i32 s22, s30, 0x58
	v_lshl_add_u64 v[68:69], v[66:67], 0, s[22:23]
	v_lshl_add_u64 v[70:71], s[30:31], 2, v[68:69]
	global_load_dword v54, v[68:69], off
	global_load_dword v41, v[70:71], off
.LBB0_210:
	s_or_b64 exec, exec, s[38:39]
	v_mov_b32_e32 v58, s23
	s_and_saveexec_b64 s[38:39], s[34:35]
	s_xor_b64 s[38:39], exec, s[38:39]
	v_mov_b32_e32 v39, s23
	s_andn2_saveexec_b64 s[38:39], s[38:39]
	s_mul_i32 s22, s30, 0x60
	v_lshl_add_u64 v[68:69], v[66:67], 0, s[22:23]
	v_lshl_add_u64 v[70:71], s[30:31], 2, v[68:69]
	global_load_dword v58, v[68:69], off
	global_load_dword v39, v[70:71], off
.LBB0_214:
	s_or_b64 exec, exec, s[38:39]
	v_mov_b32_e32 v60, s23
	s_and_saveexec_b64 s[38:39], s[34:35]
	s_xor_b64 s[38:39], exec, s[38:39]
	v_mov_b32_e32 v37, s23
	s_andn2_saveexec_b64 s[38:39], s[38:39]
	s_mul_i32 s22, s30, 0x68
	v_lshl_add_u64 v[68:69], v[66:67], 0, s[22:23]
	v_lshl_add_u64 v[70:71], s[30:31], 2, v[68:69]
	global_load_dword v60, v[68:69], off
	global_load_dword v37, v[70:71], off
.LBB0_218:
	s_or_b64 exec, exec, s[38:39]
	v_mov_b32_e32 v62, s23
	s_and_saveexec_b64 s[38:39], s[34:35]
	s_xor_b64 s[38:39], exec, s[38:39]
	v_mov_b32_e32 v35, s23
	s_andn2_saveexec_b64 s[38:39], s[38:39]
	s_mul_i32 s22, s30, 0x70
	v_lshl_add_u64 v[68:69], v[66:67], 0, s[22:23]
	v_lshl_add_u64 v[70:71], s[30:31], 2, v[68:69]
	global_load_dword v62, v[68:69], off
	global_load_dword v35, v[70:71], off
.LBB0_222:
	s_or_b64 exec, exec, s[38:39]
	v_mov_b32_e32 v64, s23
	s_and_saveexec_b64 s[38:39], s[34:35]
	s_xor_b64 s[34:35], exec, s[38:39]
	v_mov_b32_e32 v63, s23
	s_andn2_saveexec_b64 s[34:35], s[34:35]
	s_mul_i32 s22, s30, 0x78
	v_lshl_add_u64 v[66:67], v[66:67], 0, s[22:23]
	v_lshl_add_u64 v[68:69], s[30:31], 2, v[66:67]
	global_load_dword v64, v[66:67], off
	global_load_dword v63, v[68:69], off
.LBB0_226:
	s_or_b64 exec, exec, s[34:35]
	s_cmp_eq_u64 s[24:25], 0
	s_cselect_b32 s98, s16, s24
	s_cselect_b32 s99, s17, s25
	v_lshlrev_b32_e32 v114, 2, v78
	s_nop 3
	global_load_dwordx4 v[128:131], v114, s[98:99] offset:16
	global_load_dwordx4 v[124:127], v114, s[98:99]
	s_waitcnt vmcnt(34)
	v_mov_b64_e32 v[92:93], s[28:29]
.LBB0_227:
	v_add_u32_e32 v97, 0x400, v96
	v_add_u32_e32 v98, 0x800, v96
	v_add_u32_e32 v99, 0xc00, v96
	v_add_u32_e32 v100, 0x1000, v96
	v_add_u32_e32 v101, 0x1400, v96
	v_add_u32_e32 v102, 0x1800, v96
	v_add_u32_e32 v103, 0x1c00, v96
	ds_write2_b32 v96, v2, v1 offset1:66
	ds_write2_b32 v96, v4, v3 offset0:132 offset1:198
	ds_write2_b32 v97, v6, v5 offset0:8 offset1:74
	ds_write2_b32 v97, v8, v7 offset0:140 offset1:206
	ds_write2_b32 v98, v10, v9 offset0:16 offset1:82
	ds_write2_b32 v98, v12, v11 offset0:148 offset1:214
	ds_write2_b32 v99, v14, v13 offset0:24 offset1:90
	ds_write2_b32 v99, v16, v15 offset0:156 offset1:222
	ds_write2_b32 v100, v18, v17 offset0:32 offset1:98
	ds_write2_b32 v100, v22, v19 offset0:164 offset1:230
	ds_write2_b32 v101, v26, v21 offset0:40 offset1:106
	ds_write2_b32 v101, v32, v23 offset0:172 offset1:238
	ds_write2_b32 v102, v38, v25 offset0:48 offset1:114
	ds_write2_b32 v102, v44, v27 offset0:180 offset1:246
	ds_write2_b32 v103, v50, v29 offset0:56 offset1:122
	ds_write2_b32 v103, v56, v31 offset0:188 offset1:254
	s_waitcnt lgkmcnt(0)
	s_cmp_eq_u64 s[20:21], 0
	s_cbranch_scc1 .LBB0_229
	v_mov_b32_e32 v66, v120
	v_mov_b32_e32 v67, v121
	v_mov_b32_e32 v68, v122
	v_mov_b32_e32 v69, v123
	v_mov_b32_e32 v70, v116
	v_mov_b32_e32 v71, v117
	v_mov_b32_e32 v72, v118
	v_mov_b32_e32 v73, v119
	v_mov_b32_e32 v94, v67
	v_mov_b32_e32 v67, v68
	v_mov_b32_e32 v95, v69
	v_mov_b32_e32 v68, v71
	v_mov_b32_e32 v71, v72
	v_mov_b32_e32 v69, v73
	s_branch .LBB0_230

.LBB0_271:
	s_xor_b64 s[30:31], s[30:31], -1
	v_mov_b32_e32 v2, s23
	s_and_saveexec_b64 s[34:35], s[30:31]
	s_xor_b64 s[34:35], exec, s[34:35]
	v_mov_b32_e32 v1, s23
	s_or_saveexec_b64 s[34:35], s[34:35]
	v_lshl_add_u64 v[66:67], v[66:67], 0, v[76:77]
	s_xor_b64 exec, exec, s[34:35]
	v_lshl_add_u64 v[4:5], s[28:29], 2, v[66:67]
	global_load_dword v2, v[66:67], off
	global_load_dword v1, v[4:5], off
.LBB0_275:
	s_or_b64 exec, exec, s[34:35]
	v_mov_b32_e32 v4, s23
	s_and_saveexec_b64 s[34:35], s[30:31]
	s_xor_b64 s[34:35], exec, s[34:35]
	v_mov_b32_e32 v3, s23
	s_andn2_saveexec_b64 s[34:35], s[34:35]
	v_lshl_add_u64 v[68:69], s[28:29], 3, v[66:67]
	v_lshl_add_u64 v[70:71], s[28:29], 2, v[68:69]
	global_load_dword v4, v[68:69], off
	global_load_dword v3, v[70:71], off
.LBB0_279:
	s_or_b64 exec, exec, s[34:35]
	v_mov_b32_e32 v6, s23
	s_and_saveexec_b64 s[34:35], s[30:31]
	s_xor_b64 s[34:35], exec, s[34:35]
	v_mov_b32_e32 v5, s23
	s_andn2_saveexec_b64 s[34:35], s[34:35]
	v_lshl_add_u64 v[68:69], s[28:29], 4, v[66:67]
	v_lshl_add_u64 v[70:71], s[28:29], 2, v[68:69]
	global_load_dword v6, v[68:69], off
	global_load_dword v5, v[70:71], off
.LBB0_283:
	s_or_b64 exec, exec, s[34:35]
	v_mov_b32_e32 v8, s23
	s_and_saveexec_b64 s[34:35], s[30:31]
	s_xor_b64 s[34:35], exec, s[34:35]
	v_mov_b32_e32 v7, s23
	s_andn2_saveexec_b64 s[34:35], s[34:35]
	s_mul_i32 s22, s28, 24
	v_lshl_add_u64 v[68:69], v[66:67], 0, s[22:23]
	v_lshl_add_u64 v[70:71], s[28:29], 2, v[68:69]
	global_load_dword v8, v[68:69], off
	global_load_dword v7, v[70:71], off
.LBB0_287:
	s_or_b64 exec, exec, s[34:35]
	v_mov_b32_e32 v10, s23
	s_and_saveexec_b64 s[34:35], s[30:31]
	s_xor_b64 s[34:35], exec, s[34:35]
	v_mov_b32_e32 v9, s23
	s_andn2_saveexec_b64 s[34:35], s[34:35]
	s_lshl_b64 s[38:39], s[28:29], 5
	v_lshl_add_u64 v[68:69], v[66:67], 0, s[38:39]
	v_lshl_add_u64 v[70:71], s[28:29], 2, v[68:69]
	global_load_dword v10, v[68:69], off
	global_load_dword v9, v[70:71], off
.LBB0_291:
	s_or_b64 exec, exec, s[34:35]
	v_mov_b32_e32 v12, s23
	s_and_saveexec_b64 s[34:35], s[30:31]
	s_xor_b64 s[34:35], exec, s[34:35]
	v_mov_b32_e32 v11, s23
	s_andn2_saveexec_b64 s[34:35], s[34:35]
	s_mul_i32 s22, s28, 40
	v_lshl_add_u64 v[68:69], v[66:67], 0, s[22:23]
	v_lshl_add_u64 v[70:71], s[28:29], 2, v[68:69]
	global_load_dword v12, v[68:69], off
	global_load_dword v11, v[70:71], off
.LBB0_295:
	s_or_b64 exec, exec, s[34:35]
	v_mov_b32_e32 v14, s23
	s_and_saveexec_b64 s[34:35], s[30:31]
	s_xor_b64 s[34:35], exec, s[34:35]
	v_mov_b32_e32 v13, s23
	s_andn2_saveexec_b64 s[34:35], s[34:35]
	s_mul_i32 s22, s28, 48
	v_lshl_add_u64 v[68:69], v[66:67], 0, s[22:23]
	v_lshl_add_u64 v[70:71], s[28:29], 2, v[68:69]
	global_load_dword v14, v[68:69], off
	global_load_dword v13, v[70:71], off
.LBB0_299:
	s_or_b64 exec, exec, s[34:35]
	v_mov_b32_e32 v16, s23
	s_and_saveexec_b64 s[34:35], s[30:31]
	s_xor_b64 s[34:35], exec, s[34:35]
	v_mov_b32_e32 v15, s23
	s_andn2_saveexec_b64 s[34:35], s[34:35]
	s_mul_i32 s22, s28, 56
	v_lshl_add_u64 v[68:69], v[66:67], 0, s[22:23]
	v_lshl_add_u64 v[70:71], s[28:29], 2, v[68:69]
	global_load_dword v16, v[68:69], off
	global_load_dword v15, v[70:71], off
.LBB0_303:
	s_or_b64 exec, exec, s[34:35]
	v_mov_b32_e32 v18, s23
	s_and_saveexec_b64 s[34:35], s[30:31]
	s_xor_b64 s[34:35], exec, s[34:35]
	v_mov_b32_e32 v17, s23
	s_andn2_saveexec_b64 s[34:35], s[34:35]
	s_lshl_b64 s[38:39], s[28:29], 6
	v_lshl_add_u64 v[68:69], v[66:67], 0, s[38:39]
	v_lshl_add_u64 v[70:71], s[28:29], 2, v[68:69]
	global_load_dword v18, v[68:69], off
	global_load_dword v17, v[70:71], off
.LBB0_307:
	s_or_b64 exec, exec, s[34:35]
	v_mov_b32_e32 v22, s23
	s_and_saveexec_b64 s[34:35], s[30:31]
	s_xor_b64 s[34:35], exec, s[34:35]
	v_mov_b32_e32 v19, s23
	s_andn2_saveexec_b64 s[34:35], s[34:35]
	s_mul_i32 s22, s28, 0x48
	v_lshl_add_u64 v[68:69], v[66:67], 0, s[22:23]
	v_lshl_add_u64 v[70:71], s[28:29], 2, v[68:69]
	global_load_dword v22, v[68:69], off
	global_load_dword v19, v[70:71], off
.LBB0_311:
	s_or_b64 exec, exec, s[34:35]
	v_mov_b32_e32 v26, s23
	s_and_saveexec_b64 s[34:35], s[30:31]
	s_xor_b64 s[34:35], exec, s[34:35]
	v_mov_b32_e32 v21, s23
	s_andn2_saveexec_b64 s[34:35], s[34:35]
	s_mul_i32 s22, s28, 0x50
	v_lshl_add_u64 v[68:69], v[66:67], 0, s[22:23]
	v_lshl_add_u64 v[70:71], s[28:29], 2, v[68:69]
	global_load_dword v26, v[68:69], off
	global_load_dword v21, v[70:71], off
.LBB0_315:
	s_or_b64 exec, exec, s[34:35]
	v_mov_b32_e32 v32, s23
	s_and_saveexec_b64 s[34:35], s[30:31]
	s_xor_b64 s[34:35], exec, s[34:35]
	v_mov_b32_e32 v23, s23
	s_andn2_saveexec_b64 s[34:35], s[34:35]
	s_mul_i32 s22, s28, 0x58
	v_lshl_add_u64 v[68:69], v[66:67], 0, s[22:23]
	v_lshl_add_u64 v[70:71], s[28:29], 2, v[68:69]
	global_load_dword v32, v[68:69], off
	global_load_dword v23, v[70:71], off
.LBB0_319:
	s_or_b64 exec, exec, s[34:35]
	v_mov_b32_e32 v38, s23
	s_and_saveexec_b64 s[34:35], s[30:31]
	s_xor_b64 s[34:35], exec, s[34:35]
	v_mov_b32_e32 v25, s23
	s_andn2_saveexec_b64 s[34:35], s[34:35]
	s_mul_i32 s22, s28, 0x60
	v_lshl_add_u64 v[68:69], v[66:67], 0, s[22:23]
	v_lshl_add_u64 v[70:71], s[28:29], 2, v[68:69]
	global_load_dword v38, v[68:69], off
	global_load_dword v25, v[70:71], off
.LBB0_323:
	s_or_b64 exec, exec, s[34:35]
	v_mov_b32_e32 v44, s23
	s_and_saveexec_b64 s[34:35], s[30:31]
	s_xor_b64 s[34:35], exec, s[34:35]
	v_mov_b32_e32 v27, s23
	s_andn2_saveexec_b64 s[34:35], s[34:35]
	s_mul_i32 s22, s28, 0x68
	v_lshl_add_u64 v[68:69], v[66:67], 0, s[22:23]
	v_lshl_add_u64 v[70:71], s[28:29], 2, v[68:69]
	global_load_dword v44, v[68:69], off
	global_load_dword v27, v[70:71], off
.LBB0_327:
	s_or_b64 exec, exec, s[34:35]
	v_mov_b32_e32 v50, s23
	s_and_saveexec_b64 s[34:35], s[30:31]
	s_xor_b64 s[34:35], exec, s[34:35]
	v_mov_b32_e32 v29, s23
	s_andn2_saveexec_b64 s[34:35], s[34:35]
	s_mul_i32 s22, s28, 0x70
	v_lshl_add_u64 v[68:69], v[66:67], 0, s[22:23]
	v_lshl_add_u64 v[70:71], s[28:29], 2, v[68:69]
	global_load_dword v50, v[68:69], off
	global_load_dword v29, v[70:71], off
.LBB0_331:
	s_or_b64 exec, exec, s[34:35]
	v_mov_b32_e32 v56, s23
	s_and_saveexec_b64 s[34:35], s[30:31]
	s_xor_b64 s[30:31], exec, s[34:35]
	v_mov_b32_e32 v31, s23
	s_andn2_saveexec_b64 s[30:31], s[30:31]
	s_mul_i32 s22, s28, 0x78
	v_lshl_add_u64 v[66:67], v[66:67], 0, s[22:23]
	v_lshl_add_u64 v[68:69], s[28:29], 2, v[66:67]
	global_load_dword v56, v[66:67], off
	global_load_dword v31, v[68:69], off
	s_branch .LBB0_120
